# gate phase prologue: 8 gate-weight row loads batched before LDS writes (stacked on v15)
# baseline (speedup 1.0000x reference)
; #define LAS __attribute__((address_space(3)))
; DI void gla_gate_phase(int wv, LAS unsigned char* lds, const float* x, const float* w_in, const float* w2, const float* bg, const bf16_t* qk1,
;                        bf16_t* qd, bf16_t* ki, bf16_t* kst, float* decay, bf16_t* sbuf) {
;     ...
;     for (int i = 0; i < 8; ++i) { const int idx = tid + 512 * i, k = idx >> 2, n4 = (idx & 3) * 4; *(LAS f32x4*)(wg + k * 16 + n4) = *(const f32x4*)(w_in + (size_t)k * 3088 + 3072 + n4); }
;     __syncthreads();
;     const int c = tid;
;     float w2c[16];
; #pragma unroll
;     for (int j = 0; j < 16; ++j) w2c[j] = w2[j * 512 + c];
;     const float bc = bg[c];
.LBB0_137:
	v_writelane_b32 v254, s30, 34
	s_andn2_b64 vcc, exec, s[0:1]
	v_mov_b32_e32 v167, v252
	v_writelane_b32 v254, s31, 35
	s_cbranch_vccnz .LBB0_182
	v_readlane_b32 s0, v253, 54
	v_readlane_b32 s1, v253, 55
	s_load_dwordx4 s[4:7], s[0:1], 0x0
	s_mov_b32 s0, s68
	v_mov_b32_e32 v2, v232
	s_waitcnt lgkmcnt(0)
	v_mov_b64_e32 v[8:9], s[4:5]
	v_lshl_add_u32 v18, s0, 6, v2
	v_lshlrev_b32_e32 v0, 4, v2
	v_ashrrev_i32_e32 v10, 2, v18
	s_movk_i32 s2, 0x3040
	v_and_b32_e32 v0, 48, v0
	v_mad_i64_i32 v[4:5], s[0:1], v10, s2, v[8:9]
	v_lshl_add_u64 v[4:5], v[4:5], 0, v[0:1]
	v_add_co_u32_e32 v4, vcc, s88, v4
	s_mov_b32 s56, s55
	s_nop 0
	v_addc_co_u32_e32 v5, vcc, 0, v5, vcc
	global_load_dwordx4 v[136:139], v[4:5], off
	v_add_u32_e32 v3, 0, v0
	v_lshl_add_u32 v10, v10, 6, v3
	s_cmpk_gt_i32 s56, 0x1ff
	v_mov_b32_e32 v180, v10
	s_nop 0
	v_add_u32_e32 v4, 0x200, v18
	v_ashrrev_i32_e32 v10, 2, v4
	v_mad_i64_i32 v[4:5], s[0:1], v10, s2, v[8:9]
	v_lshl_add_u64 v[4:5], v[4:5], 0, v[0:1]
	v_add_co_u32_e32 v4, vcc, s88, v4
	v_lshl_add_u32 v10, v10, 6, v3
	s_nop 0
	v_addc_co_u32_e32 v5, vcc, 0, v5, vcc
	global_load_dwordx4 v[140:143], v[4:5], off
	v_mov_b32_e32 v181, v10
	s_nop 0
	v_add_u32_e32 v4, 0x400, v18
	v_ashrrev_i32_e32 v10, 2, v4
	v_mad_i64_i32 v[4:5], s[0:1], v10, s2, v[8:9]
	v_lshl_add_u64 v[4:5], v[4:5], 0, v[0:1]
	v_add_co_u32_e32 v4, vcc, s88, v4
	v_lshl_add_u32 v10, v10, 6, v3
	s_nop 0
	v_addc_co_u32_e32 v5, vcc, 0, v5, vcc
	global_load_dwordx4 v[144:147], v[4:5], off
	v_mov_b32_e32 v182, v10
	s_nop 0
	v_add_u32_e32 v4, 0x600, v18
	v_ashrrev_i32_e32 v10, 2, v4
	v_mad_i64_i32 v[4:5], s[0:1], v10, s2, v[8:9]
	v_lshl_add_u64 v[4:5], v[4:5], 0, v[0:1]
	v_add_co_u32_e32 v4, vcc, s88, v4
	v_lshl_add_u32 v10, v10, 6, v3
	s_nop 0
	v_addc_co_u32_e32 v5, vcc, 0, v5, vcc
	global_load_dwordx4 v[148:151], v[4:5], off
	v_mov_b32_e32 v183, v10
	s_nop 0
	v_add_u32_e32 v4, 0x800, v18
	v_ashrrev_i32_e32 v10, 2, v4
	v_mad_i64_i32 v[4:5], s[0:1], v10, s2, v[8:9]
	v_lshl_add_u64 v[4:5], v[4:5], 0, v[0:1]
	v_add_co_u32_e32 v4, vcc, s88, v4
	v_lshl_add_u32 v10, v10, 6, v3
	s_nop 0
	v_addc_co_u32_e32 v5, vcc, 0, v5, vcc
	global_load_dwordx4 v[152:155], v[4:5], off
	v_mov_b32_e32 v184, v10
	s_nop 0
	v_add_u32_e32 v4, 0xa00, v18
	v_ashrrev_i32_e32 v10, 2, v4
	v_mad_i64_i32 v[4:5], s[0:1], v10, s2, v[8:9]
	v_lshl_add_u64 v[4:5], v[4:5], 0, v[0:1]
	v_add_co_u32_e32 v4, vcc, s88, v4
	v_lshl_add_u32 v10, v10, 6, v3
	s_nop 0
	v_addc_co_u32_e32 v5, vcc, 0, v5, vcc
	global_load_dwordx4 v[156:159], v[4:5], off
	v_mov_b32_e32 v185, v10
	s_nop 0
	v_add_u32_e32 v4, 0xc00, v18
	v_ashrrev_i32_e32 v10, 2, v4
	v_mad_i64_i32 v[4:5], s[0:1], v10, s2, v[8:9]
	v_lshl_add_u64 v[4:5], v[4:5], 0, v[0:1]
	v_add_co_u32_e32 v4, vcc, s88, v4
	v_lshl_add_u32 v10, v10, 6, v3
	s_nop 0
	v_addc_co_u32_e32 v5, vcc, 0, v5, vcc
	global_load_dwordx4 v[160:163], v[4:5], off
	v_mov_b32_e32 v186, v10
	s_nop 0
	v_add_u32_e32 v4, 0xe00, v18
	v_ashrrev_i32_e32 v10, 2, v4
	v_mad_i64_i32 v[4:5], s[0:1], v10, s2, v[8:9]
	v_lshl_add_u64 v[4:5], v[4:5], 0, v[0:1]
	v_add_co_u32_e32 v4, vcc, 0x3000, v4
	v_lshl_add_u32 v0, v10, 6, v3
	s_nop 0
	v_addc_co_u32_e32 v5, vcc, 0, v5, vcc
	global_load_dwordx4 v[176:179], v[4:5], off
	v_mov_b32_e32 v187, v0
	s_nop 0
	s_waitcnt vmcnt(0)
	ds_write_b128 v180, v[136:139]
	ds_write_b128 v181, v[140:143]
	ds_write_b128 v182, v[144:147]
	ds_write_b128 v183, v[148:151]
	ds_write_b128 v184, v[152:155]
	ds_write_b128 v185, v[156:159]
	ds_write_b128 v186, v[160:163]
	ds_write_b128 v187, v[176:179]
	s_waitcnt lgkmcnt(0)
	s_barrier
	s_cbranch_scc1 .LBB0_153
	v_ashrrev_i32_e32 v19, 31, v18
	v_lshlrev_b64 v[4:5], 2, v[18:19]
	v_lshl_add_u64 v[6:7], s[6:7], 0, v[4:5]
	v_add_co_u32_e32 v8, vcc, 0x1000, v6
	global_load_dword v20, v[6:7], off
	global_load_dword v22, v[6:7], off offset:2048
	v_addc_co_u32_e32 v9, vcc, 0, v7, vcc
	global_load_dword v24, v[8:9], off
	global_load_dword v26, v[8:9], off offset:2048
	v_add_co_u32_e32 v8, vcc, 0x2000, v6
	v_readlane_b32 s0, v253, 54
	s_nop 0
	v_addc_co_u32_e32 v9, vcc, 0, v7, vcc
	global_load_dword v21, v[8:9], off
	global_load_dword v23, v[8:9], off offset:2048
	v_add_co_u32_e32 v8, vcc, 0x3000, v6
	v_readlane_b32 s1, v253, 55
	s_nop 0
	v_addc_co_u32_e32 v9, vcc, 0, v7, vcc
	global_load_dword v25, v[8:9], off
	global_load_dword v27, v[8:9], off offset:2048
	v_add_co_u32_e32 v8, vcc, 0x4000, v6
	v_ashrrev_i32_e32 v12, 6, v18
	s_nop 0
	v_addc_co_u32_e32 v9, vcc, 0, v7, vcc
	global_load_dword v28, v[8:9], off
	global_load_dword v30, v[8:9], off offset:2048
	v_add_co_u32_e32 v8, vcc, 0x5000, v6
	v_and_b32_e32 v0, 1, v12
	s_nop 0
	v_addc_co_u32_e32 v9, vcc, 0, v7, vcc
	global_load_dword v32, v[8:9], off
	global_load_dword v34, v[8:9], off offset:2048
	v_add_co_u32_e32 v8, vcc, 0x6000, v6
	v_bfe_u32 v11, v2, 5, 1
	s_nop 0
	v_addc_co_u32_e32 v9, vcc, 0, v7, vcc
	v_add_co_u32_e32 v6, vcc, 0x7000, v6
	global_load_dword v29, v[8:9], off
	global_load_dword v31, v[8:9], off offset:2048
	v_addc_co_u32_e32 v7, vcc, 0, v7, vcc
	global_load_dword v33, v[6:7], off
	global_load_dword v35, v[6:7], off offset:2048
	s_load_dwordx2 s[0:1], s[0:1], 0x10
	v_and_b32_e32 v6, 0xffffff80, v18
	v_ashrrev_i32_e32 v7, 31, v6
	v_lshlrev_b64 v[6:7], 1, v[6:7]
	v_and_b32_e32 v36, 31, v2
	s_waitcnt lgkmcnt(0)
; #define LAS __attribute__((address_space(3)))
; DI void gla_gate_phase(int wv, LAS unsigned char* lds, const float* x, const float* w_in, const float* w2, const float* bg, const bf16_t* qk1,
;                        bf16_t* qd, bf16_t* ki, bf16_t* kst, float* decay, bf16_t* sbuf) {
;     ...
;             for (int n = 0; n < 16; ++n) { const float s0 = wave_sum(a0[n]), s1 = wave_sum(a1[n]); v0 = (lane == n) ? s0 : v0; v1 = (lane == n) ? s1 : v1; }
;             if (lane < 16) { gl[(wid * 8 + tt) * 16 + lane] = v0; gl[(wid * 8 + tt + 1) * 16 + lane] = v1; }
;         }
;         __syncthreads();
;         float cum = 0.f;
; #pragma unroll 4
;         for (int t = 0; t < 64; ++t) { float z = bc;
; #pragma unroll
;             for (int q = 0; q < 4; ++q) { const f32x4 gv = *(const LAS f32x4*)(gl + t * 16 + 4 * q); z += gv.x * w2c[4 * q] + gv.y * w2c[4 * q + 1] + gv.z * w2c[4 * q + 2] + gv.w * w2c[4 * q + 3]; }
;             cum += logsig(z) * 0.0625f; }
;         const float blast = cum;
;         decay[((size_t)b * 64 + ch) * 512 + c] = __expf(blast);
;         cum = 0.f;
;         for (int t8 = 0; t8 < 64; t8 += 8) {
;             float ksv[8];
; #pragma unroll
;             for (int u = 0; u < 8; ++u) { const int t = t8 + u; float z = bc;
; #pragma unroll
;                 for (int q = 0; q < 4; ++q) { const f32x4 gv = *(const LAS f32x4*)(gl + t * 16 + 4 * q); z += gv.x * w2c[4 * q] + gv.y * w2c[4 * q + 1] + gv.z * w2c[4 * q + 2] + gv.w * w2c[4 * q + 3]; }
;                 cum += logsig(z) * 0.0625f;
;                 const size_t tok = T0 + t;
;                 const float qv = bf2f(qk1[tok * 1024 + c]), kv = bf2f(qk1[tok * 1024 + 512 + c]);
;                 qd[tok * 512 + c] = f2bf(qv * 0.08838834764831845f * __expf(cum));
;                 ki[tok * 512 + c] = f2bf(kv * __expf(-cum));
;                 ksv[u] = kv * __expf(blast - cum); }
;             u32x4 w; w.x = pk2(ksv[0], ksv[1]); w.y = pk2(ksv[2], ksv[3]); w.z = pk2(ksv[4], ksv[5]); w.w = pk2(ksv[6], ksv[7]);
;             *(u32x4*)(kst + ((size_t)b * 512 + c) * SEQ + ch * 64 + t8) = w;
;         }
;         __syncthreads();
;         const int hd = wid >> 1;
; #pragma unroll
;         for (int u = 0; u < 2; ++u) {
;             const int tt2 = (wid & 1) * 2 + u, kt = tt2 >> 1, qt = tt2 & 1;
;             f32x16 S = zero16();
;             if (!(kt == 1 && qt == 0)) {
; #pragma unroll
	v_lshl_add_u64 v[4:5], s[0:1], 0, v[4:5]
	v_cmp_eq_u32_e64 s[0:1], 0, v0
	global_load_dword v37, v[4:5], off
	v_ashrrev_i32_e32 v4, 7, v18
	v_writelane_b32 v254, s0, 36
	v_ashrrev_i32_e32 v5, 31, v4
	v_lshlrev_b64 v[40:41], 6, v[4:5]
	v_writelane_b32 v254, s1, 37
	v_readlane_b32 s0, v253, 50
	v_lshlrev_b32_e32 v5, 5, v0
	v_lshlrev_b32_e32 v0, 6, v0
	v_readlane_b32 s1, v253, 51
	v_lshlrev_b32_e32 v4, 2, v11
	v_or_b32_e32 v48, v36, v5
	v_lshl_add_u64 v[42:43], s[0:1], 0, v[0:1]
	v_readlane_b32 s0, v253, 42
	v_readlane_b32 s1, v253, 43
	v_lshlrev_b32_e32 v0, 4, v11
	v_and_b32_e32 v10, 63, v2
	v_lshl_add_u64 v[8:9], s[0:1], 0, v[6:7]
	v_readlane_b32 s0, v253, 46
	v_readlane_b32 s1, v253, 47
	v_lshl_add_u64 v[44:45], v[8:9], 0, v[0:1]
	v_or_b32_e32 v9, 32, v36
	v_lshl_add_u64 v[6:7], s[0:1], 0, v[6:7]
	v_lshl_add_u64 v[46:47], v[6:7], 0, v[0:1]
	v_or_b32_e32 v0, v5, v4
	v_or_b32_e32 v7, 24, v0
	v_cmp_gt_u32_e64 s[0:1], v7, v9
	v_or_b32_e32 v5, 2, v0
	v_or_b32_e32 v11, 3, v0
	v_writelane_b32 v254, s0, 38
	v_or_b32_e32 v50, 8, v0
	v_or_b32_e32 v51, 10, v0
	v_writelane_b32 v254, s1, 39
	v_cmp_gt_u32_e64 s[0:1], v0, v36
	v_or_b32_e32 v52, 11, v0
	v_or_b32_e32 v53, 16, v0
	v_writelane_b32 v254, s0, 40
	v_or_b32_e32 v54, 18, v0
	v_or_b32_e32 v55, 19, v0
	v_writelane_b32 v254, s1, 41
	v_cmp_lt_u32_e64 s[0:1], v0, v36
	v_or_b32_e32 v56, 26, v0
	v_or_b32_e32 v57, 27, v0
	v_writelane_b32 v254, s0, 42
	v_cmp_gt_u32_e64 s[42:43], 16, v10
	v_lshlrev_b32_e32 v49, 6, v10
	v_writelane_b32 v254, s1, 43
	v_cmp_gt_u32_e64 s[0:1], v5, v36
	v_cmp_eq_u32_e64 s[8:9], 15, v10
	v_cmp_eq_u32_e64 s[10:11], 14, v10
	v_writelane_b32 v254, s0, 44
	v_cmp_eq_u32_e64 s[12:13], 13, v10
	v_cmp_eq_u32_e64 s[14:15], 12, v10
	v_writelane_b32 v254, s1, 45
	v_cmp_gt_u32_e64 s[0:1], v11, v36
	v_cmp_eq_u32_e64 s[16:17], 11, v10
	v_cmp_eq_u32_e64 s[18:19], 10, v10
	v_writelane_b32 v254, s0, 46
	v_cmp_eq_u32_e64 s[20:21], 9, v10
	v_cmp_eq_u32_e64 s[22:23], 8, v10
	v_writelane_b32 v254, s1, 47
	v_cmp_gt_u32_e64 s[0:1], v50, v36
	v_cmp_eq_u32_e64 s[24:25], 7, v10
	v_cmp_eq_u32_e64 s[26:27], 6, v10
	v_writelane_b32 v254, s0, 48
	v_cmp_eq_u32_e64 s[28:29], 5, v10
	v_cmp_eq_u32_e64 s[30:31], 4, v10
	v_writelane_b32 v254, s1, 49
	v_cmp_lt_u32_e64 s[0:1], v50, v36
	v_cmp_eq_u32_e64 s[34:35], 3, v10
	v_cmp_eq_u32_e64 s[36:37], 2, v10
	v_writelane_b32 v254, s0, 50
	v_cmp_eq_u32_e64 s[38:39], 1, v10
	v_cmp_eq_u32_e64 s[40:41], 0, v10
	v_writelane_b32 v254, s1, 51
	v_cmp_gt_u32_e64 s[0:1], v51, v36
	v_or_b32_e32 v58, 0x500, v10
	v_or_b32_e32 v60, 0x540, v10
	v_writelane_b32 v254, s0, 52
	v_or_b32_e32 v62, 0x580, v10
	v_or_b32_e32 v64, 0x5c0, v10
	v_writelane_b32 v254, s1, 53
	v_cmp_gt_u32_e64 s[0:1], v52, v36
	v_or_b32_e32 v66, 0x600, v10
	v_or_b32_e32 v68, 0x640, v10
	v_writelane_b32 v254, s0, 54
	v_or_b32_e32 v70, 0x680, v10
	v_or_b32_e32 v72, 0x6c0, v10
	v_writelane_b32 v254, s1, 55
	v_cmp_gt_u32_e64 s[0:1], v53, v36
	v_or_b32_e32 v74, 0x700, v10
	v_or_b32_e32 v76, 0x740, v10
	v_writelane_b32 v254, s0, 56
	v_or_b32_e32 v78, 0x780, v10
	v_or_b32_e32 v80, 0x7c0, v10
	v_writelane_b32 v254, s1, 57
	v_cmp_lt_u32_e64 s[0:1], v53, v36
	v_lshlrev_b32_e32 v38, 3, v12
	v_lshlrev_b64 v[2:3], 13, v[18:19]
	v_writelane_b32 v254, s0, 58
	v_lshlrev_b32_e32 v6, 6, v9
	v_or_b32_e32 v13, 0x1000, v49
	v_writelane_b32 v254, s1, 59
	v_cmp_gt_u32_e64 s[0:1], v54, v36
	v_or_b32_e32 v14, 0x2000, v49
	v_or_b32_e32 v15, 0x3000, v49
	v_writelane_b32 v254, s0, 60
	v_or_b32_e32 v16, 0x4000, v49
	v_or_b32_e32 v17, 0x5000, v49
	v_writelane_b32 v254, s1, 61
	v_cmp_gt_u32_e64 s[0:1], v55, v36
	v_or_b32_e32 v63, 0x6000, v49
	v_or_b32_e32 v65, 0x7000, v49
; DI void gla_gate_phase(int wv, LAS unsigned char* lds, const float* x, const float* w_in, const float* w2, const float* bg, const bf16_t* qk1,
;                        bf16_t* qd, bf16_t* ki, bf16_t* kst, float* decay, bf16_t* sbuf) {
;     ...
;             for (int i = 0; i < 16; ++i) { const int k = lane + 64 * i; const float x0 = x[t0 * DM + k], x1 = x[(t0 + 1) * DM + k];
; #pragma unroll
;                 for (int q = 0; q < 4; ++q) { const f32x4 w = *(const LAS f32x4*)(wg + k * 16 + 4 * q);
;                     a0[4 * q] += x0 * w.x; a0[4 * q + 1] += x0 * w.y; a0[4 * q + 2] += x0 * w.z; a0[4 * q + 3] += x0 * w.w;
;                     a1[4 * q] += x1 * w.x; a1[4 * q + 1] += x1 * w.y; a1[4 * q + 2] += x1 * w.z; a1[4 * q + 3] += x1 * w.w; } }
;             float v0 = 0.f, v1 = 0.f;
; #pragma unroll
;             for (int n = 0; n < 16; ++n) { const float s0 = wave_sum(a0[n]), s1 = wave_sum(a1[n]); v0 = (lane == n) ? s0 : v0; v1 = (lane == n) ? s1 : v1; }
;             if (lane < 16) { gl[(wid * 8 + tt) * 16 + lane] = v0; gl[(wid * 8 + tt + 1) * 16 + lane] = v1; }
;         }
;         __syncthreads();
;         float cum = 0.f;
; #pragma unroll 4
;         for (int t = 0; t < 64; ++t) { float z = bc;
; #pragma unroll
;             for (int q = 0; q < 4; ++q) { const f32x4 gv = *(const LAS f32x4*)(gl + t * 16 + 4 * q); z += gv.x * w2c[4 * q] + gv.y * w2c[4 * q + 1] + gv.z * w2c[4 * q + 2] + gv.w * w2c[4 * q + 3]; }
;             cum += logsig(z) * 0.0625f; }
;         const float blast = cum;
;         decay[((size_t)b * 64 + ch) * 512 + c] = __expf(blast);
;         cum = 0.f;
;         for (int t8 = 0; t8 < 64; t8 += 8) {
;             float ksv[8];
; #pragma unroll
;             for (int u = 0; u < 8; ++u) { const int t = t8 + u; float z = bc;
; #pragma unroll
;                 for (int q = 0; q < 4; ++q) { const f32x4 gv = *(const LAS f32x4*)(gl + t * 16 + 4 * q); z += gv.x * w2c[4 * q] + gv.y * w2c[4 * q + 1] + gv.z * w2c[4 * q + 2] + gv.w * w2c[4 * q + 3]; }
;                 cum += logsig(z) * 0.0625f;
;                 const size_t tok = T0 + t;
;                 const float qv = bf2f(qk1[tok * 1024 + c]), kv = bf2f(qk1[tok * 1024 + 512 + c]);
;                 qd[tok * 512 + c] = f2bf(qv * 0.08838834764831845f * __expf(cum));
;                 ki[tok * 512 + c] = f2bf(kv * __expf(-cum));
;                 ksv[u] = kv * __expf(blast - cum); }
	v_writelane_b32 v254, s0, 62
	v_or_b32_e32 v67, 0x8000, v49
	v_or_b32_e32 v69, 0x9000, v49
	v_writelane_b32 v254, s1, 63
	v_cmp_gt_u32_e64 s[0:1], v7, v36
	v_or_b32_e32 v71, 0xa000, v49
	v_or_b32_e32 v73, 0xb000, v49
	v_writelane_b32 v255, s0, 0
	v_or_b32_e32 v75, 0xc000, v49
	v_or_b32_e32 v77, 0xd000, v49
	v_writelane_b32 v255, s1, 1
	v_cmp_lt_u32_e64 s[0:1], v7, v36
	v_or_b32_e32 v79, 0xe000, v49
	v_or_b32_e32 v81, 0xf000, v49
	v_writelane_b32 v255, s0, 2
	v_lshlrev_b32_e32 v8, 6, v36
	s_add_i32 s4, 0, 0x10000
	v_writelane_b32 v255, s1, 3
	v_cmp_gt_u32_e64 s[0:1], v56, v36
	v_ashrrev_i32_e32 v39, 31, v38
	v_add_u32_e32 v59, 0, v16
	v_writelane_b32 v255, s0, 4
	v_add_u32_e32 v61, 0, v17
	v_add_u32_e32 v63, 0, v63
	v_writelane_b32 v255, s1, 5
	v_cmp_gt_u32_e64 s[0:1], v57, v36
	v_add_u32_e32 v65, 0, v65
	v_add_u32_e32 v67, 0, v67
	v_writelane_b32 v255, s0, 6
	v_add_u32_e32 v69, 0, v69
	v_add_u32_e32 v71, 0, v71
	v_writelane_b32 v255, s1, 7
	v_cmp_gt_u32_e64 s[0:1], v0, v9
	v_add_u32_e32 v73, 0, v73
	v_add_u32_e32 v75, 0, v75
	v_writelane_b32 v255, s0, 8
	v_add_u32_e32 v77, 0, v77
	v_add_u32_e32 v79, 0, v79
	v_writelane_b32 v255, s1, 9
	v_cmp_lt_u32_e64 s[0:1], v0, v9
	v_lshlrev_b32_e32 v0, 2, v10
	v_lshl_add_u64 v[82:83], s[52:53], 0, v[0:1]
	v_writelane_b32 v255, s0, 10
	v_add_u32_e32 v81, 0, v81
	v_lshlrev_b32_e32 v92, 1, v4
	v_writelane_b32 v255, s1, 11
	v_cmp_gt_u32_e64 s[0:1], v5, v9
	v_lshl_or_b32 v5, v12, 9, v0
	v_lshlrev_b32_e32 v0, 1, v8
	v_writelane_b32 v255, s0, 12
	v_lshlrev_b32_e32 v94, 1, v6
	s_mov_b32 s7, s56
	v_writelane_b32 v255, s1, 13
	v_cmp_gt_u32_e64 s[0:1], v11, v9
	s_nop 1
	v_writelane_b32 v255, s0, 14
	s_nop 1
	v_writelane_b32 v255, s1, 15
	v_cmp_gt_u32_e64 s[0:1], v50, v9
	s_nop 1
	v_writelane_b32 v255, s0, 16
	s_nop 1
	v_writelane_b32 v255, s1, 17
	v_cmp_lt_u32_e64 s[0:1], v50, v9
	v_or_b32_e32 v50, 0x400, v10
	s_nop 0
	v_writelane_b32 v255, s0, 18
	s_nop 1
	v_writelane_b32 v255, s1, 19
	v_cmp_gt_u32_e64 s[0:1], v51, v9
	v_add_u32_e32 v51, s4, v5
	s_nop 0
	v_writelane_b32 v255, s0, 20
	s_nop 1
	v_writelane_b32 v255, s1, 21
	v_cmp_gt_u32_e64 s[0:1], v52, v9
	v_or_b32_e32 v52, 0x440, v10
	s_nop 0
	v_writelane_b32 v255, s0, 22
	s_nop 1
	v_writelane_b32 v255, s1, 23
	v_cmp_gt_u32_e64 s[0:1], v53, v9
	s_nop 1
	v_writelane_b32 v255, s0, 24
	s_nop 1
	v_writelane_b32 v255, s1, 25
	v_cmp_lt_u32_e64 s[0:1], v53, v9
	v_add_u32_e32 v53, 0, v13
	s_nop 0
	v_writelane_b32 v255, s0, 26
	s_nop 1
	v_writelane_b32 v255, s1, 27
	v_cmp_gt_u32_e64 s[0:1], v54, v9
	v_or_b32_e32 v54, 0x480, v10
	s_nop 0
	v_writelane_b32 v255, s0, 28
	s_nop 1
	v_writelane_b32 v255, s1, 29
	v_cmp_gt_u32_e64 s[0:1], v55, v9
	v_add_u32_e32 v55, 0, v14
	s_nop 0
	v_writelane_b32 v255, s0, 30
	s_nop 1
	v_writelane_b32 v255, s1, 31
	v_cmp_lt_u32_e64 s[0:1], v7, v9
	s_nop 1
	v_writelane_b32 v255, s0, 32
	s_nop 1
	v_writelane_b32 v255, s1, 33
	v_cmp_gt_u32_e64 s[0:1], v56, v9
	v_or_b32_e32 v56, 0x4c0, v10
	v_lshlrev_b64 v[10:11], 1, v[18:19]
	v_writelane_b32 v255, s0, 34
	s_nop 1
	v_writelane_b32 v255, s1, 35
	v_cmp_gt_u32_e64 s[0:1], v57, v9
	v_add_u32_e32 v57, 0, v15
	s_nop 0
	v_writelane_b32 v255, s0, 36
	s_nop 1
	v_writelane_b32 v255, s1, 37
	v_readlane_b32 s0, v253, 28
	v_readlane_b32 s1, v253, 29
	s_nop 1
	v_lshl_add_u64 v[84:85], s[0:1], 0, v[10:11]
	v_readlane_b32 s0, v253, 60
	v_readlane_b32 s1, v253, 61
	s_nop 1
	v_lshl_add_u64 v[86:87], s[0:1], 0, v[10:11]
	v_readlane_b32 s0, v253, 56
	v_readlane_b32 s1, v253, 57
	s_nop 1
	v_lshl_add_u64 v[88:89], s[0:1], 0, v[10:11]
	v_readlane_b32 s0, v254, 0
	v_readlane_b32 s1, v254, 1
	s_nop 1
	v_lshl_add_u64 v[90:91], s[0:1], 0, v[2:3]
	s_branch .LBB0_141
